# diff-item lam dot-product loop unrolled with double-buffered loads; attention loop back-edges merged into one conditional branch
# speedup vs baseline: 1.0417x; 1.0011x over previous
; #define MFMA32(a, b, c) __builtin_amdgcn_mfma_f32_32x32x16_bf16((a), (b), (c), 0, 0, 0)
; DI u32 pack2(float a, float b) { f2_t v = {a, b}; bf2_t r = __builtin_convertvector(v, bf2_t); return __builtin_bit_cast(u32, r); }
; DI float shx(float v, int k) { return __int_as_float(__builtin_amdgcn_ds_bpermute((lane_id_l() ^ k) << 2, __float_as_int(v))); }
;     ...
;     } else if (MODE == 1) {
;       float ls = 0.f;
; #pragma unroll
;       for (int t2 = 0; t2 < 2; ++t2)
; #pragma unroll
;         for (int e = 0; e < 16; ++e) { float p = __builtin_amdgcn_exp2f(st[t2][e]); st[t2][e] = p; ls += p; }
;       l_run += ls;
;     } else {
;       float mx = st[0][0];
; #pragma unroll
;       for (int t2 = 0; t2 < 2; ++t2)
; #pragma unroll
;         for (int e = 0; e < 16; ++e) mx = fmaxf(mx, st[t2][e]);
;       mx = fmaxf(mx, shx(mx, 32));
;       float mnew = fmaxf(m_run, mx);
;       float alpha = __builtin_amdgcn_exp2f(m_run - mnew);
;       const bool changed = mnew > m_run;
;       m_run = mnew;
;       float ls = 0.f;
; #pragma unroll
;       for (int t2 = 0; t2 < 2; ++t2)
; #pragma unroll
;         for (int e = 0; e < 16; ++e) { float p = __builtin_amdgcn_exp2f(st[t2][e] - mnew); st[t2][e] = p; ls += p; }
;       l_run = l_run * alpha + ls;
;       if (__any(changed)) {
; #pragma unroll
;         for (int dt = 0; dt < 4; ++dt)
; #pragma unroll
;           for (int e = 0; e < 16; ++e) o[dt][e] *= alpha;
;       }
;     }
; #pragma unroll
;     for (int c = 0; c < 4; ++c) {
;       const int t2 = c >> 1, s2 = c & 1;
;       if (c + 1 < 4) {
; #pragma unroll
;         for (int dt = 0; dt < 4; ++dt) vf[(c + 1) & 1][dt] = *(const bf16x8*)(Vs + (32 * dt + r) * 72 + 16 * (c + 1) + 8 * h);
;       }
;       u32x4 pk;
;       pk.x = pack2(st[t2][8 * s2], st[t2][8 * s2 + 1]); pk.y = pack2(st[t2][8 * s2 + 2], st[t2][8 * s2 + 3]);
;       pk.z = pack2(st[t2][8 * s2 + 4], st[t2][8 * s2 + 5]); pk.w = pack2(st[t2][8 * s2 + 6], st[t2][8 * s2 + 7]);
;       bf16x8 pf = __builtin_bit_cast(bf16x8, pk);
;       __builtin_amdgcn_sched_barrier(0);
; #pragma unroll
;       for (int dt = 0; dt < 4; ++dt) o[dt] = MFMA32(vf[c & 1][dt], pf, o[dt]);
;       __builtin_amdgcn_sched_barrier(0);
;     }
;     if (kt + 1 < nkt) lstore((kt + 1) & 1);
;     if (kt + 2 < nkt) gload((kt0 + kt + 2) * 64);
;     __syncthreads();
.Ldiff_skip_gb:
	v_mfma_f32_32x32x16_bf16 v[34:49], v[178:181], v[246:249], v[34:49]
	ds_read_b128 v[178:181], v160 offset:8768
	v_lshl_add_u64 v[154:155], v[154:155], 0, s[30:31]
	v_lshl_add_u64 v[156:157], v[156:157], 0, s[90:91]
	v_lshl_add_u64 v[158:159], v[158:159], 0, s[90:91]
	v_add_f32_e32 v166, v92, v166
	v_add_f32_e32 v166, v93, v166
	v_mfma_f32_32x32x16_bf16 v[18:33], v[182:185], v[246:249], v[18:33]
	ds_read_b128 v[182:185], v160 offset:8800
	v_add_f32_e32 v166, v94, v166
	v_add_f32_e32 v166, v95, v166
	v_add_f32_e32 v166, v96, v166
	v_add_f32_e32 v166, v97, v166
	v_add_f32_e32 v147, v147, v166
	s_waitcnt lgkmcnt(11)
	v_mfma_f32_32x32x16_bf16 v[82:97], v[170:173], v[114:117], v[66:81]
	v_exp_f32_e32 v98, v98
	v_exp_f32_e32 v99, v99
	v_exp_f32_e32 v100, v100
	s_waitcnt lgkmcnt(10)
	v_mfma_f32_32x32x16_bf16 v[82:97], v[174:177], v[118:121], v[82:97]
	ds_read_b128 v[170:173], v153 offset:17440
	v_exp_f32_e32 v101, v101
	v_exp_f32_e32 v102, v102
	v_exp_f32_e32 v103, v103
	s_waitcnt lgkmcnt(2)
	v_mfma_f32_32x32x16_bf16 v[82:97], v[178:181], v[122:125], v[82:97]
	ds_read_b128 v[174:177], v153 offset:22048
	v_exp_f32_e32 v104, v104
	v_exp_f32_e32 v105, v105
	v_cvt_pk_bf16_f32 v202, v98, v99
	v_cvt_pk_bf16_f32 v203, v100, v101
	v_cvt_pk_bf16_f32 v204, v102, v103
	v_cvt_pk_bf16_f32 v205, v104, v105
	s_waitcnt lgkmcnt(2)
	v_mfma_f32_32x32x16_bf16 v[82:97], v[182:185], v[126:129], v[82:97]
	ds_read_b128 v[178:181], v153 offset:26656
	v_exp_f32_e32 v106, v106
	v_exp_f32_e32 v107, v107
	v_exp_f32_e32 v108, v108
	v_mfma_f32_32x32x16_bf16 v[2:17], v[186:189], v[202:205], v[2:17]
	ds_read_b128 v[182:185], v153 offset:31264
	ds_read_b128 v[186:189], v153 offset:17472
	v_exp_f32_e32 v109, v109
	v_exp_f32_e32 v110, v110
	v_exp_f32_e32 v111, v111
	v_mfma_f32_32x32x16_bf16 v[50:65], v[190:193], v[202:205], v[50:65]
	ds_read_b128 v[190:193], v153 offset:22080
	v_exp_f32_e32 v112, v112
	v_exp_f32_e32 v113, v113
	v_add_f32_e32 v160, v98, v99
	v_add_f32_e32 v160, v100, v160
	v_mfma_f32_32x32x16_bf16 v[34:49], v[194:197], v[202:205], v[34:49]
	ds_read_b128 v[194:197], v153 offset:26688
	v_cvt_pk_bf16_f32 v246, v106, v107
	v_cvt_pk_bf16_f32 v247, v108, v109
	v_cvt_pk_bf16_f32 v248, v110, v111
	v_cvt_pk_bf16_f32 v249, v112, v113
	v_add_f32_e32 v160, v101, v160
	v_add_f32_e32 v160, v102, v160
	v_mfma_f32_32x32x16_bf16 v[18:33], v[198:201], v[202:205], v[18:33]
	ds_read_b128 v[198:201], v153 offset:31296
	v_exp_f32_e32 v82, v82
	v_exp_f32_e32 v83, v83
	v_exp_f32_e32 v84, v84
	s_waitcnt lgkmcnt(7)
	v_mfma_f32_32x32x16_bf16 v[2:17], v[170:173], v[246:249], v[2:17]
	ds_read_b128 v[170:173], v153 offset:17504
	v_exp_f32_e32 v85, v85
	v_exp_f32_e32 v86, v86
	v_exp_f32_e32 v87, v87
	s_waitcnt lgkmcnt(7)
	v_mfma_f32_32x32x16_bf16 v[50:65], v[174:177], v[246:249], v[50:65]
	ds_read_b128 v[174:177], v153 offset:22112
	v_exp_f32_e32 v88, v88
	v_exp_f32_e32 v89, v89
	v_cvt_pk_bf16_f32 v202, v82, v83
	v_add_f32_e32 v160, v103, v160
	s_waitcnt lgkmcnt(7)
	v_mfma_f32_32x32x16_bf16 v[34:49], v[178:181], v[246:249], v[34:49]
	ds_read_b128 v[178:181], v153 offset:26720
	v_cvt_pk_bf16_f32 v203, v84, v85
	v_cvt_pk_bf16_f32 v204, v86, v87
	v_cvt_pk_bf16_f32 v205, v88, v89
	v_exp_f32_e32 v90, v90
	v_add_f32_e32 v160, v104, v160
	s_waitcnt lgkmcnt(7)
	v_mfma_f32_32x32x16_bf16 v[18:33], v[182:185], v[246:249], v[18:33]
	ds_read_b128 v[182:185], v153 offset:31328
	v_exp_f32_e32 v91, v91
	v_exp_f32_e32 v92, v92
	v_exp_f32_e32 v93, v93
	s_waitcnt lgkmcnt(7)
	v_mfma_f32_32x32x16_bf16 v[2:17], v[186:189], v[202:205], v[2:17]
	v_exp_f32_e32 v94, v94
	v_exp_f32_e32 v95, v95
	v_exp_f32_e32 v96, v96
	s_waitcnt lgkmcnt(6)
	v_mfma_f32_32x32x16_bf16 v[50:65], v[190:193], v[202:205], v[50:65]
	v_exp_f32_e32 v97, v97
	v_add_f32_e32 v160, v105, v160
	v_add_f32_e32 v160, v106, v160
	v_add_f32_e32 v160, v107, v160
	v_add_f32_e32 v160, v108, v160
	v_add_f32_e32 v160, v109, v160
	s_waitcnt lgkmcnt(5)
	v_mfma_f32_32x32x16_bf16 v[34:49], v[194:197], v[202:205], v[34:49]
	v_cvt_pk_bf16_f32 v246, v90, v91
	v_cvt_pk_bf16_f32 v247, v92, v93
	v_cvt_pk_bf16_f32 v248, v94, v95
	v_cvt_pk_bf16_f32 v249, v96, v97
	v_add_f32_e32 v160, v110, v160
	v_add_f32_e32 v160, v111, v160
	s_waitcnt lgkmcnt(4)
	v_mfma_f32_32x32x16_bf16 v[18:33], v[198:201], v[202:205], v[18:33]
	v_add_f32_e32 v160, v112, v160
	v_add_f32_e32 v160, v113, v160
	v_add_f32_e32 v147, v147, v160
	s_cmp_lg_u32 s71, 64
	s_waitcnt lgkmcnt(0)
	s_mov_b32 s70, s71
	s_barrier
	s_cbranch_scc1 .LBB0_560

; DI void diff_attn_item(const Params& P, const WsPtrs& W, int layer, int item, unsigned char* smem) {
;     ...
;     const float* lp = P.in[I_DLAM] + layer * 256;
;     float s1 = 0.f, s2 = 0.f;
;     for (int i = 0; i < 64; ++i) { s1 += lp[i] * lp[64 + i]; s2 += lp[128 + i] * lp[192 + i]; }
.LBB0_582:
	global_load_dwordx4 v[72:75], v1, s[78:79] offset:48
	global_load_dwordx4 v[76:79], v1, s[78:79] offset:32
	global_load_dwordx4 v[80:83], v1, s[78:79] offset:16
	global_load_dwordx4 v[84:87], v1, s[78:79]
	global_load_dwordx4 v[88:91], v1, s[78:79] offset:304
	global_load_dwordx4 v[92:95], v1, s[78:79] offset:288
	global_load_dwordx4 v[96:99], v1, s[78:79] offset:272
	global_load_dwordx4 v[100:103], v1, s[78:79] offset:256
	global_load_dwordx4 v[104:107], v1, s[78:79] offset:560
	global_load_dwordx4 v[108:111], v1, s[78:79] offset:544
	global_load_dwordx4 v[112:115], v1, s[78:79] offset:528
	global_load_dwordx4 v[116:119], v1, s[78:79] offset:512
	global_load_dwordx4 v[120:123], v1, s[78:79] offset:816
	global_load_dwordx4 v[124:127], v1, s[78:79] offset:800
	global_load_dwordx4 v[128:131], v1, s[78:79] offset:784
	global_load_dwordx4 v[132:135], v1, s[78:79] offset:768
	global_load_dwordx4 v[140:143], v1, s[78:79] offset:112
	global_load_dwordx4 v[144:147], v1, s[78:79] offset:96
	global_load_dwordx4 v[148:151], v1, s[78:79] offset:80
	global_load_dwordx4 v[152:155], v1, s[78:79] offset:64
	global_load_dwordx4 v[156:159], v1, s[78:79] offset:368
	global_load_dwordx4 v[176:179], v1, s[78:79] offset:352
	global_load_dwordx4 v[180:183], v1, s[78:79] offset:336
	global_load_dwordx4 v[184:187], v1, s[78:79] offset:320
	global_load_dwordx4 v[188:191], v1, s[78:79] offset:624
	global_load_dwordx4 v[192:195], v1, s[78:79] offset:608
	global_load_dwordx4 v[196:199], v1, s[78:79] offset:592
	global_load_dwordx4 v[200:203], v1, s[78:79] offset:576
	global_load_dwordx4 v[204:207], v1, s[78:79] offset:880
	global_load_dwordx4 v[208:211], v1, s[78:79] offset:864
	global_load_dwordx4 v[212:215], v1, s[78:79] offset:848
	global_load_dwordx4 v[216:219], v1, s[78:79] offset:832
	s_waitcnt vmcnt(16)
	v_mov_b32_e32 v137, v84
	v_mov_b32_e32 v139, v100
	v_mov_b32_e32 v136, v116
	v_mov_b32_e32 v84, v117
	v_mov_b32_e32 v138, v132
	v_pk_fma_f32 v[70:71], v[136:137], v[138:139], v[70:71]
	v_mov_b32_e32 v100, v133
	v_pk_fma_f32 v[70:71], v[84:85], v[100:101], v[70:71]
	v_mov_b32_e32 v84, v118
	v_mov_b32_e32 v85, v86
	v_mov_b32_e32 v100, v134
	v_mov_b32_e32 v101, v102
	v_pk_fma_f32 v[70:71], v[84:85], v[100:101], v[70:71]
	v_mov_b32_e32 v86, v119
	v_mov_b32_e32 v102, v135
	v_pk_fma_f32 v[70:71], v[86:87], v[102:103], v[70:71]
	v_mov_b32_e32 v84, v112
	v_mov_b32_e32 v85, v80
	v_mov_b32_e32 v86, v128
	v_mov_b32_e32 v87, v96
	v_pk_fma_f32 v[70:71], v[84:85], v[86:87], v[70:71]
	v_mov_b32_e32 v80, v113
	v_mov_b32_e32 v96, v129
	v_pk_fma_f32 v[70:71], v[80:81], v[96:97], v[70:71]
	v_mov_b32_e32 v80, v114
	v_mov_b32_e32 v81, v82
	v_mov_b32_e32 v84, v130
	v_mov_b32_e32 v85, v98
	v_pk_fma_f32 v[70:71], v[80:81], v[84:85], v[70:71]
	v_mov_b32_e32 v82, v115
	v_mov_b32_e32 v98, v131
	v_pk_fma_f32 v[70:71], v[82:83], v[98:99], v[70:71]
	v_mov_b32_e32 v80, v108
	v_mov_b32_e32 v81, v76
	v_mov_b32_e32 v82, v124
	v_mov_b32_e32 v83, v92
	v_pk_fma_f32 v[70:71], v[80:81], v[82:83], v[70:71]
	v_mov_b32_e32 v76, v109
	v_mov_b32_e32 v92, v125
	v_pk_fma_f32 v[70:71], v[76:77], v[92:93], v[70:71]
	v_mov_b32_e32 v76, v110
	v_mov_b32_e32 v77, v78
	v_mov_b32_e32 v80, v126
	v_mov_b32_e32 v81, v94
	v_pk_fma_f32 v[70:71], v[76:77], v[80:81], v[70:71]
	v_mov_b32_e32 v78, v111
	v_mov_b32_e32 v94, v127
	v_pk_fma_f32 v[70:71], v[78:79], v[94:95], v[70:71]
	v_mov_b32_e32 v76, v104
	v_mov_b32_e32 v77, v72
	v_mov_b32_e32 v78, v120
	v_mov_b32_e32 v79, v88
	v_pk_fma_f32 v[70:71], v[76:77], v[78:79], v[70:71]
	v_mov_b32_e32 v72, v105
	v_mov_b32_e32 v88, v121
	v_pk_fma_f32 v[70:71], v[72:73], v[88:89], v[70:71]
	v_mov_b32_e32 v72, v106
	v_mov_b32_e32 v73, v74
	v_mov_b32_e32 v76, v122
	v_mov_b32_e32 v77, v90
	v_pk_fma_f32 v[70:71], v[72:73], v[76:77], v[70:71]
	v_mov_b32_e32 v74, v107
	v_mov_b32_e32 v90, v123
	v_pk_fma_f32 v[70:71], v[74:75], v[90:91], v[70:71]
	global_load_dwordx4 v[72:75], v1, s[78:79] offset:176
	global_load_dwordx4 v[76:79], v1, s[78:79] offset:160
	global_load_dwordx4 v[80:83], v1, s[78:79] offset:144
	global_load_dwordx4 v[84:87], v1, s[78:79] offset:128
	global_load_dwordx4 v[88:91], v1, s[78:79] offset:432
	global_load_dwordx4 v[92:95], v1, s[78:79] offset:416
	global_load_dwordx4 v[96:99], v1, s[78:79] offset:400
	global_load_dwordx4 v[100:103], v1, s[78:79] offset:384
	global_load_dwordx4 v[104:107], v1, s[78:79] offset:688
	global_load_dwordx4 v[108:111], v1, s[78:79] offset:672
	global_load_dwordx4 v[112:115], v1, s[78:79] offset:656
	global_load_dwordx4 v[116:119], v1, s[78:79] offset:640
	global_load_dwordx4 v[120:123], v1, s[78:79] offset:944
	global_load_dwordx4 v[124:127], v1, s[78:79] offset:928
	global_load_dwordx4 v[128:131], v1, s[78:79] offset:912
	global_load_dwordx4 v[132:135], v1, s[78:79] offset:896
	s_waitcnt vmcnt(16)
; DI void diff_attn_item(const Params& P, const WsPtrs& W, int layer, int item, unsigned char* smem) {
;     ...
;     const float* lp = P.in[I_DLAM] + layer * 256;
;     float s1 = 0.f, s2 = 0.f;
;     for (int i = 0; i < 64; ++i) { s1 += lp[i] * lp[64 + i]; s2 += lp[128 + i] * lp[192 + i]; }
	v_mov_b32_e32 v137, v152
	v_mov_b32_e32 v139, v184
	v_mov_b32_e32 v136, v200
	v_mov_b32_e32 v152, v201
	v_mov_b32_e32 v138, v216
	v_pk_fma_f32 v[70:71], v[136:137], v[138:139], v[70:71]
	v_mov_b32_e32 v184, v217
	v_pk_fma_f32 v[70:71], v[152:153], v[184:185], v[70:71]
	v_mov_b32_e32 v152, v202
	v_mov_b32_e32 v153, v154
	v_mov_b32_e32 v184, v218
	v_mov_b32_e32 v185, v186
	v_pk_fma_f32 v[70:71], v[152:153], v[184:185], v[70:71]
	v_mov_b32_e32 v154, v203
	v_mov_b32_e32 v186, v219
	v_pk_fma_f32 v[70:71], v[154:155], v[186:187], v[70:71]
	v_mov_b32_e32 v152, v196
	v_mov_b32_e32 v153, v148
	v_mov_b32_e32 v154, v212
	v_mov_b32_e32 v155, v180
	v_pk_fma_f32 v[70:71], v[152:153], v[154:155], v[70:71]
	v_mov_b32_e32 v148, v197
	v_mov_b32_e32 v180, v213
	v_pk_fma_f32 v[70:71], v[148:149], v[180:181], v[70:71]
	v_mov_b32_e32 v148, v198
	v_mov_b32_e32 v149, v150
	v_mov_b32_e32 v152, v214
	v_mov_b32_e32 v153, v182
	v_pk_fma_f32 v[70:71], v[148:149], v[152:153], v[70:71]
	v_mov_b32_e32 v150, v199
	v_mov_b32_e32 v182, v215
	v_pk_fma_f32 v[70:71], v[150:151], v[182:183], v[70:71]
	v_mov_b32_e32 v148, v192
	v_mov_b32_e32 v149, v144
	v_mov_b32_e32 v150, v208
	v_mov_b32_e32 v151, v176
	v_pk_fma_f32 v[70:71], v[148:149], v[150:151], v[70:71]
	v_mov_b32_e32 v144, v193
	v_mov_b32_e32 v176, v209
	v_pk_fma_f32 v[70:71], v[144:145], v[176:177], v[70:71]
	v_mov_b32_e32 v144, v194
	v_mov_b32_e32 v145, v146
	v_mov_b32_e32 v148, v210
	v_mov_b32_e32 v149, v178
	v_pk_fma_f32 v[70:71], v[144:145], v[148:149], v[70:71]
	v_mov_b32_e32 v146, v195
	v_mov_b32_e32 v178, v211
	v_pk_fma_f32 v[70:71], v[146:147], v[178:179], v[70:71]
	v_mov_b32_e32 v144, v188
	v_mov_b32_e32 v145, v140
	v_mov_b32_e32 v146, v204
	v_mov_b32_e32 v147, v156
	v_pk_fma_f32 v[70:71], v[144:145], v[146:147], v[70:71]
	v_mov_b32_e32 v140, v189
	v_mov_b32_e32 v156, v205
	v_pk_fma_f32 v[70:71], v[140:141], v[156:157], v[70:71]
	v_mov_b32_e32 v140, v190
	v_mov_b32_e32 v141, v142
	v_mov_b32_e32 v144, v206
	v_mov_b32_e32 v145, v158
	v_pk_fma_f32 v[70:71], v[140:141], v[144:145], v[70:71]
	v_mov_b32_e32 v142, v191
	v_mov_b32_e32 v158, v207
	v_pk_fma_f32 v[70:71], v[142:143], v[158:159], v[70:71]
	global_load_dwordx4 v[140:143], v1, s[78:79] offset:240
	global_load_dwordx4 v[144:147], v1, s[78:79] offset:224
	global_load_dwordx4 v[148:151], v1, s[78:79] offset:208
	global_load_dwordx4 v[152:155], v1, s[78:79] offset:192
	global_load_dwordx4 v[156:159], v1, s[78:79] offset:496
	global_load_dwordx4 v[176:179], v1, s[78:79] offset:480
	global_load_dwordx4 v[180:183], v1, s[78:79] offset:464
	global_load_dwordx4 v[184:187], v1, s[78:79] offset:448
	global_load_dwordx4 v[188:191], v1, s[78:79] offset:752
	global_load_dwordx4 v[192:195], v1, s[78:79] offset:736
	global_load_dwordx4 v[196:199], v1, s[78:79] offset:720
	global_load_dwordx4 v[200:203], v1, s[78:79] offset:704
	global_load_dwordx4 v[204:207], v1, s[78:79] offset:1008
	global_load_dwordx4 v[208:211], v1, s[78:79] offset:992
	global_load_dwordx4 v[212:215], v1, s[78:79] offset:976
	global_load_dwordx4 v[216:219], v1, s[78:79] offset:960
	s_waitcnt vmcnt(16)
	v_mov_b32_e32 v137, v84
	v_mov_b32_e32 v139, v100
	v_mov_b32_e32 v136, v116
	v_mov_b32_e32 v84, v117
	v_mov_b32_e32 v138, v132
	v_pk_fma_f32 v[70:71], v[136:137], v[138:139], v[70:71]
	v_mov_b32_e32 v100, v133
	v_pk_fma_f32 v[70:71], v[84:85], v[100:101], v[70:71]
	v_mov_b32_e32 v84, v118
	v_mov_b32_e32 v85, v86
	v_mov_b32_e32 v100, v134
	v_mov_b32_e32 v101, v102
	v_pk_fma_f32 v[70:71], v[84:85], v[100:101], v[70:71]
	v_mov_b32_e32 v86, v119
	v_mov_b32_e32 v102, v135
	v_pk_fma_f32 v[70:71], v[86:87], v[102:103], v[70:71]
	v_mov_b32_e32 v84, v112
	v_mov_b32_e32 v85, v80
	v_mov_b32_e32 v86, v128
	v_mov_b32_e32 v87, v96
	v_pk_fma_f32 v[70:71], v[84:85], v[86:87], v[70:71]
	v_mov_b32_e32 v80, v113
	v_mov_b32_e32 v96, v129
	v_pk_fma_f32 v[70:71], v[80:81], v[96:97], v[70:71]
	v_mov_b32_e32 v80, v114
	v_mov_b32_e32 v81, v82
	v_mov_b32_e32 v84, v130
	v_mov_b32_e32 v85, v98
	v_pk_fma_f32 v[70:71], v[80:81], v[84:85], v[70:71]
	v_mov_b32_e32 v82, v115
	v_mov_b32_e32 v98, v131
	v_pk_fma_f32 v[70:71], v[82:83], v[98:99], v[70:71]
	v_mov_b32_e32 v80, v108
	v_mov_b32_e32 v81, v76
	v_mov_b32_e32 v82, v124
	v_mov_b32_e32 v83, v92
	v_pk_fma_f32 v[70:71], v[80:81], v[82:83], v[70:71]
	v_mov_b32_e32 v76, v109
	v_mov_b32_e32 v92, v125
	v_pk_fma_f32 v[70:71], v[76:77], v[92:93], v[70:71]
	v_mov_b32_e32 v76, v110
	v_mov_b32_e32 v77, v78
	v_mov_b32_e32 v80, v126
	v_mov_b32_e32 v81, v94
	v_pk_fma_f32 v[70:71], v[76:77], v[80:81], v[70:71]
	v_mov_b32_e32 v78, v111
	v_mov_b32_e32 v94, v127
	v_pk_fma_f32 v[70:71], v[78:79], v[94:95], v[70:71]
	v_mov_b32_e32 v76, v104
	v_mov_b32_e32 v77, v72
	v_mov_b32_e32 v78, v120
	v_mov_b32_e32 v79, v88
	v_pk_fma_f32 v[70:71], v[76:77], v[78:79], v[70:71]
	v_mov_b32_e32 v72, v105
	v_mov_b32_e32 v88, v121
	v_pk_fma_f32 v[70:71], v[72:73], v[88:89], v[70:71]
	v_mov_b32_e32 v72, v106
	v_mov_b32_e32 v73, v74
	v_mov_b32_e32 v76, v122
	v_mov_b32_e32 v77, v90
	v_pk_fma_f32 v[70:71], v[72:73], v[76:77], v[70:71]
	v_mov_b32_e32 v74, v107
	v_mov_b32_e32 v90, v123
	v_pk_fma_f32 v[70:71], v[74:75], v[90:91], v[70:71]
	s_waitcnt vmcnt(0)
; DI int launder_s(int v) { asm volatile("" : "+s"(v)); return v; }
; DI void diff_attn_item(const Params& P, const WsPtrs& W, int layer, int item, unsigned char* smem) {
;     ...
;     for (int i = 0; i < 64; ++i) { s1 += lp[i] * lp[64 + i]; s2 += lp[128 + i] * lp[192 + i]; }
;     const float lam_init = (launder_s(layer) == 0) ? 0.2f : (0.8f - 0.6f * 0.7408182206817179f);
;     const float lam = __expf(s1) - __expf(s2) + lam_init;
;     float ss = 0.f;
; #pragma unroll
;     for (int dt = 0; dt < 4; ++dt)
; #pragma unroll
;       for (int e = 0; e < 16; ++e) {
;         float v = o[dt][e] * inv - lam * ex[((w & 3) * 64 + dt * 16 + e) * 64 + lane];
;         o[dt][e] = v; ss += v * v;
	v_mov_b32_e32 v137, v152
	v_mov_b32_e32 v139, v184
	v_mov_b32_e32 v136, v200
	v_mov_b32_e32 v152, v201
	v_mov_b32_e32 v138, v216
	v_pk_fma_f32 v[70:71], v[136:137], v[138:139], v[70:71]
	v_mov_b32_e32 v184, v217
	v_pk_fma_f32 v[70:71], v[152:153], v[184:185], v[70:71]
	v_mov_b32_e32 v152, v202
	v_mov_b32_e32 v153, v154
	v_mov_b32_e32 v184, v218
	v_mov_b32_e32 v185, v186
	v_pk_fma_f32 v[70:71], v[152:153], v[184:185], v[70:71]
	v_mov_b32_e32 v154, v203
	v_mov_b32_e32 v186, v219
	v_pk_fma_f32 v[70:71], v[154:155], v[186:187], v[70:71]
	v_mov_b32_e32 v152, v196
	v_mov_b32_e32 v153, v148
	v_mov_b32_e32 v154, v212
	v_mov_b32_e32 v155, v180
	v_pk_fma_f32 v[70:71], v[152:153], v[154:155], v[70:71]
	v_mov_b32_e32 v148, v197
	v_mov_b32_e32 v180, v213
	v_pk_fma_f32 v[70:71], v[148:149], v[180:181], v[70:71]
	v_mov_b32_e32 v148, v198
	v_mov_b32_e32 v149, v150
	v_mov_b32_e32 v152, v214
	v_mov_b32_e32 v153, v182
	v_pk_fma_f32 v[70:71], v[148:149], v[152:153], v[70:71]
	v_mov_b32_e32 v150, v199
	v_mov_b32_e32 v182, v215
	v_pk_fma_f32 v[70:71], v[150:151], v[182:183], v[70:71]
	v_mov_b32_e32 v148, v192
	v_mov_b32_e32 v149, v144
	v_mov_b32_e32 v150, v208
	v_mov_b32_e32 v151, v176
	v_pk_fma_f32 v[70:71], v[148:149], v[150:151], v[70:71]
	v_mov_b32_e32 v144, v193
	v_mov_b32_e32 v176, v209
	v_pk_fma_f32 v[70:71], v[144:145], v[176:177], v[70:71]
	v_mov_b32_e32 v144, v194
	v_mov_b32_e32 v145, v146
	v_mov_b32_e32 v148, v210
	v_mov_b32_e32 v149, v178
	v_pk_fma_f32 v[70:71], v[144:145], v[148:149], v[70:71]
	v_mov_b32_e32 v146, v195
	v_mov_b32_e32 v178, v211
	v_pk_fma_f32 v[70:71], v[146:147], v[178:179], v[70:71]
	v_mov_b32_e32 v144, v188
	v_mov_b32_e32 v145, v140
	v_mov_b32_e32 v146, v204
	v_mov_b32_e32 v147, v156
	v_pk_fma_f32 v[70:71], v[144:145], v[146:147], v[70:71]
	v_mov_b32_e32 v140, v189
	v_mov_b32_e32 v156, v205
	v_pk_fma_f32 v[70:71], v[140:141], v[156:157], v[70:71]
	v_mov_b32_e32 v140, v190
	v_mov_b32_e32 v141, v142
	v_mov_b32_e32 v144, v206
	v_mov_b32_e32 v145, v158
	v_pk_fma_f32 v[70:71], v[140:141], v[144:145], v[70:71]
	v_mov_b32_e32 v142, v191
	v_mov_b32_e32 v158, v207
	v_pk_fma_f32 v[70:71], v[142:143], v[158:159], v[70:71]
	s_add_u32 s16, s22, s21
	s_addc_u32 s17, s23, s20
	s_lshl_b64 s[12:13], s[8:9], 23
	s_lshl_b64 s[14:15], s[8:9], 25
	s_add_u32 s14, s62, s14
	s_addc_u32 s15, s63, s15
	s_add_u32 s14, s14, s16
	s_addc_u32 s15, s15, s17
	s_add_u32 s12, s14, s12
	s_mul_hi_i32 s9, s8, 0x1800000
	s_mul_i32 s8, s8, 0x1800000
	s_addc_u32 s13, s15, s13
	v_mul_f32_e32 v30, 0x3fb8aa3b, v71
	v_mul_f32_e32 v67, 0x3fb8aa3b, v70
	s_add_u32 s8, s12, s8
	v_exp_f32_e32 v30, v30
	v_exp_f32_e32 v67, v67
	s_addc_u32 s9, s13, s9
	v_readlane_b32 s12, v255, 19
	s_cmp_eq_u32 s12, 0
	s_cselect_b64 vcc, -1, 0
	v_mov_b32_e32 v68, 0x3eb60549
	v_mov_b32_e32 v70, 0x3e4ccccd
	v_cndmask_b32_e32 v169, v68, v70, vcc
	v_sub_f32_e32 v30, v30, v67
	v_lshlrev_b32_e32 v68, 8, v161
	v_add_f32_e32 v67, v30, v169
	v_lshl_add_u32 v30, v163, 2, 64
	v_and_b32_e32 v70, 0xc000, v68
	v_add_u32_e32 v124, v30, v70
	ds_read2st64_b32 v[88:89], v124 offset0:4 offset1:5
	ds_read2st64_b32 v[90:91], v124 offset1:1
	ds_read2st64_b32 v[94:95], v124 offset0:6 offset1:7
	ds_read2st64_b32 v[92:93], v124 offset0:2 offset1:3
	ds_read2st64_b32 v[96:97], v124 offset0:8 offset1:9
	v_mov_b32_e32 v70, v6
	ds_read2st64_b32 v[98:99], v124 offset0:10 offset1:11
	ds_read2st64_b32 v[100:101], v124 offset0:12 offset1:13
	ds_read2st64_b32 v[102:103], v124 offset0:14 offset1:15
	s_waitcnt lgkmcnt(7)
	v_mov_b32_e32 v71, v88
	v_mul_f32_e32 v6, v67, v88
	v_pk_fma_f32 v[70:71], v[66:67], v[70:71], v[6:7] op_sel_hi:[1,1,0] neg_lo:[0,0,1] neg_hi:[0,0,1]
	v_mov_b32_e32 v88, v7
	v_mov_b32_e32 v6, v8
	s_waitcnt lgkmcnt(5)
	v_mov_b32_e32 v7, v94
	v_mul_f32_e32 v8, v67, v94
	ds_read2st64_b32 v[104:105], v124 offset0:16 offset1:17
	v_pk_fma_f32 v[72:73], v[66:67], v[6:7], v[8:9] op_sel_hi:[1,1,0] neg_lo:[0,0,1] neg_hi:[0,0,1]
	v_mov_b32_e32 v6, v10
	s_waitcnt lgkmcnt(4)
	v_mov_b32_e32 v7, v96
	v_mul_f32_e32 v8, v67, v96
	v_pk_fma_f32 v[80:81], v[66:67], v[6:7], v[8:9] op_sel_hi:[1,1,0] neg_lo:[0,0,1] neg_hi:[0,0,1]
	v_mov_b32_e32 v6, v12
	s_waitcnt lgkmcnt(3)
	v_mov_b32_e32 v7, v98
	v_mul_f32_e32 v8, v67, v98
	v_pk_fma_f32 v[78:79], v[66:67], v[6:7], v[8:9] op_sel_hi:[1,1,0] neg_lo:[0,0,1] neg_hi:[0,0,1]
	v_mov_b32_e32 v6, v14
	s_waitcnt lgkmcnt(2)
	v_mov_b32_e32 v7, v100
	v_mul_f32_e32 v8, v67, v100
	ds_read2st64_b32 v[106:107], v124 offset0:18 offset1:19
	ds_read2st64_b32 v[108:109], v124 offset0:20 offset1:21
	ds_read2st64_b32 v[110:111], v124 offset0:22 offset1:23
	v_pk_fma_f32 v[74:75], v[66:67], v[6:7], v[8:9] op_sel_hi:[1,1,0] neg_lo:[0,0,1] neg_hi:[0,0,1]
	v_mov_b32_e32 v6, v16
	s_waitcnt lgkmcnt(4)
	v_mov_b32_e32 v7, v102
	v_mul_f32_e32 v8, v67, v102
	ds_read2st64_b32 v[112:113], v124 offset0:24 offset1:25
	v_pk_fma_f32 v[76:77], v[66:67], v[6:7], v[8:9] op_sel_hi:[1,1,0] neg_lo:[0,0,1] neg_hi:[0,0,1]
	v_mov_b32_e32 v6, v50
	s_waitcnt lgkmcnt(4)
	v_mov_b32_e32 v7, v104
	v_mul_f32_e32 v8, v67, v104
	v_pk_fma_f32 v[84:85], v[66:67], v[6:7], v[8:9] op_sel_hi:[1,1,0] neg_lo:[0,0,1] neg_hi:[0,0,1]
	v_mov_b32_e32 v6, v52
	s_waitcnt lgkmcnt(3)
	v_mov_b32_e32 v7, v106
	v_mul_f32_e32 v8, v67, v106
	v_pk_fma_f32 v[82:83], v[66:67], v[6:7], v[8:9] op_sel_hi:[1,1,0] neg_lo:[0,0,1] neg_hi:[0,0,1]
	v_mov_b32_e32 v6, v54
	s_waitcnt lgkmcnt(2)
	v_mov_b32_e32 v7, v108
	v_mul_f32_e32 v8, v67, v108
	ds_read2st64_b32 v[114:115], v124 offset0:26 offset1:27
	ds_read2st64_b32 v[146:147], v124 offset0:28 offset1:29
	ds_read2st64_b32 v[152:153], v124 offset0:30 offset1:31
	v_mov_b32_e32 v104, v51
	v_pk_fma_f32 v[50:51], v[66:67], v[6:7], v[8:9] op_sel_hi:[1,1,0] neg_lo:[0,0,1] neg_hi:[0,0,1]
	v_mov_b32_e32 v6, v56
	s_waitcnt lgkmcnt(4)
; DI void diff_attn_item(const Params& P, const WsPtrs& W, int layer, int item, unsigned char* smem) {
;     ...
; #pragma unroll
;     for (int dt = 0; dt < 4; ++dt)
; #pragma unroll
;       for (int e = 0; e < 16; ++e) {
;         float v = o[dt][e] * inv - lam * ex[((w & 3) * 64 + dt * 16 + e) * 64 + lane];
;         o[dt][e] = v; ss += v * v;
;       }
	v_mov_b32_e32 v7, v110
	v_mul_f32_e32 v8, v67, v110
	ds_read2st64_b32 v[156:157], v124 offset0:32 offset1:33
	v_mov_b32_e32 v106, v53
	v_pk_fma_f32 v[52:53], v[66:67], v[6:7], v[8:9] op_sel_hi:[1,1,0] neg_lo:[0,0,1] neg_hi:[0,0,1]
	v_mov_b32_e32 v6, v58
	s_waitcnt lgkmcnt(4)
	v_mov_b32_e32 v7, v112
	v_mul_f32_e32 v8, v67, v112
	v_pk_fma_f32 v[86:87], v[66:67], v[6:7], v[8:9] op_sel_hi:[1,1,0] neg_lo:[0,0,1] neg_hi:[0,0,1]
	v_mov_b32_e32 v6, v60
	s_waitcnt lgkmcnt(3)
	v_mov_b32_e32 v7, v114
	v_mul_f32_e32 v8, v67, v114
	v_mov_b32_e32 v112, v59
	v_pk_fma_f32 v[58:59], v[66:67], v[6:7], v[8:9] op_sel_hi:[1,1,0] neg_lo:[0,0,1] neg_hi:[0,0,1]
	v_mov_b32_e32 v6, v62
	s_waitcnt lgkmcnt(2)
	v_mov_b32_e32 v7, v146
	v_mul_f32_e32 v8, v67, v146
	ds_read2st64_b32 v[154:155], v124 offset0:34 offset1:35
	ds_read2st64_b32 v[150:151], v124 offset0:36 offset1:37
	ds_read2st64_b32 v[148:149], v124 offset0:38 offset1:39
	v_mov_b32_e32 v108, v55
	v_pk_fma_f32 v[54:55], v[66:67], v[6:7], v[8:9] op_sel_hi:[1,1,0] neg_lo:[0,0,1] neg_hi:[0,0,1]
	v_mov_b32_e32 v6, v64
	s_waitcnt lgkmcnt(4)
	v_mov_b32_e32 v7, v152
	v_mul_f32_e32 v8, v67, v152
	ds_read2st64_b32 v[144:145], v124 offset0:40 offset1:41
	v_mov_b32_e32 v110, v57
	v_pk_fma_f32 v[56:57], v[66:67], v[6:7], v[8:9] op_sel_hi:[1,1,0] neg_lo:[0,0,1] neg_hi:[0,0,1]
	v_mov_b32_e32 v6, v34
	s_waitcnt lgkmcnt(4)
	v_mov_b32_e32 v7, v156
	v_mul_f32_e32 v8, v67, v156
	v_pk_fma_f32 v[116:117], v[66:67], v[6:7], v[8:9] op_sel_hi:[1,1,0] neg_lo:[0,0,1] neg_hi:[0,0,1]
	v_mov_b32_e32 v6, v36
	s_waitcnt lgkmcnt(3)
	v_mov_b32_e32 v7, v154
	v_mul_f32_e32 v8, v67, v154
	v_mov_b32_e32 v152, v65
	v_pk_fma_f32 v[64:65], v[66:67], v[6:7], v[8:9] op_sel_hi:[1,1,0] neg_lo:[0,0,1] neg_hi:[0,0,1]
	v_mov_b32_e32 v6, v38
	s_waitcnt lgkmcnt(2)
	v_mov_b32_e32 v7, v150
	v_mul_f32_e32 v8, v67, v150
	ds_read2st64_b32 v[142:143], v124 offset0:42 offset1:43
	ds_read2st64_b32 v[140:141], v124 offset0:44 offset1:45
	ds_read2st64_b32 v[138:139], v124 offset0:46 offset1:47
	v_mov_b32_e32 v114, v61
	v_pk_fma_f32 v[60:61], v[66:67], v[6:7], v[8:9] op_sel_hi:[1,1,0] neg_lo:[0,0,1] neg_hi:[0,0,1]
	v_mov_b32_e32 v6, v40
	s_waitcnt lgkmcnt(4)
	v_mov_b32_e32 v7, v148
	v_mul_f32_e32 v8, v67, v148
	v_mov_b32_e32 v146, v63
	v_pk_fma_f32 v[62:63], v[66:67], v[6:7], v[8:9] op_sel_hi:[1,1,0] neg_lo:[0,0,1] neg_hi:[0,0,1]
	v_mov_b32_e32 v6, v42
	s_waitcnt lgkmcnt(3)
	v_mov_b32_e32 v7, v144
	v_mul_f32_e32 v8, v67, v144
	v_pk_fma_f32 v[120:121], v[66:67], v[6:7], v[8:9] op_sel_hi:[1,1,0] neg_lo:[0,0,1] neg_hi:[0,0,1]
	v_mov_b32_e32 v6, v44
	s_waitcnt lgkmcnt(2)
	v_mov_b32_e32 v7, v142
	v_mul_f32_e32 v8, v67, v142
	ds_read2st64_b32 v[136:137], v124 offset0:48 offset1:49
	v_pk_fma_f32 v[118:119], v[66:67], v[6:7], v[8:9] op_sel_hi:[1,1,0] neg_lo:[0,0,1] neg_hi:[0,0,1]
	v_mov_b32_e32 v6, v46
	s_waitcnt lgkmcnt(2)
	v_mov_b32_e32 v7, v140
	v_mul_f32_e32 v8, v67, v140
	v_mov_b32_e32 v144, v43
	v_pk_fma_f32 v[42:43], v[66:67], v[6:7], v[8:9] op_sel_hi:[1,1,0] neg_lo:[0,0,1] neg_hi:[0,0,1]
	v_mov_b32_e32 v6, v48
	s_waitcnt lgkmcnt(1)
	v_mov_b32_e32 v7, v138
	v_mul_f32_e32 v8, v67, v138
	v_mov_b32_e32 v94, v9
	v_mov_b32_e32 v142, v45
	v_pk_fma_f32 v[44:45], v[66:67], v[6:7], v[8:9] op_sel_hi:[1,1,0] neg_lo:[0,0,1] neg_hi:[0,0,1]
	ds_read2st64_b32 v[134:135], v124 offset0:50 offset1:51
	ds_read2st64_b32 v[132:133], v124 offset0:52 offset1:53
	ds_read2st64_b32 v[8:9], v124 offset0:54 offset1:55
	v_mov_b32_e32 v6, v18
	s_waitcnt lgkmcnt(3)
	v_mov_b32_e32 v7, v136
	v_mul_f32_e32 v10, v67, v136
	v_pk_fma_f32 v[122:123], v[66:67], v[6:7], v[10:11] op_sel_hi:[1,1,0] neg_lo:[0,0,1] neg_hi:[0,0,1]
	v_mov_b32_e32 v6, v20
	s_waitcnt lgkmcnt(2)
	v_mov_b32_e32 v7, v134
	v_mul_f32_e32 v10, v67, v134
	v_mov_b32_e32 v138, v49
	v_pk_fma_f32 v[48:49], v[66:67], v[6:7], v[10:11] op_sel_hi:[1,1,0] neg_lo:[0,0,1] neg_hi:[0,0,1]
	v_mov_b32_e32 v6, v22
	s_waitcnt lgkmcnt(1)
	v_mov_b32_e32 v7, v132
	v_mul_f32_e32 v10, v67, v132
	v_mov_b32_e32 v140, v47
	v_pk_fma_f32 v[46:47], v[66:67], v[6:7], v[10:11] op_sel_hi:[1,1,0] neg_lo:[0,0,1] neg_hi:[0,0,1]
	v_mov_b32_e32 v6, v24
	s_waitcnt lgkmcnt(0)
	v_mov_b32_e32 v7, v8
	v_pk_mul_f32 v[130:131], v[66:67], v[6:7]
	ds_read2st64_b32 v[6:7], v124 offset0:56 offset1:57
	v_mov_b32_e32 v96, v11
	v_mov_b32_e32 v98, v13
	ds_read2st64_b32 v[10:11], v124 offset0:58 offset1:59
	ds_read2st64_b32 v[12:13], v124 offset0:60 offset1:61
	ds_read_b32 v14, v124 offset:15872
	v_mov_b32_e32 v8, v25
	v_pk_mul_f32 v[158:159], v[66:67], v[8:9]
	s_waitcnt lgkmcnt(3)
	v_mov_b32_e32 v9, v6
	v_mov_b32_e32 v6, v27
	v_pk_mul_f32 v[164:165], v[66:67], v[6:7]
	v_mov_b32_e32 v6, v28
	s_waitcnt lgkmcnt(2)
	v_mov_b32_e32 v7, v10
	v_pk_mul_f32 v[124:125], v[66:67], v[6:7]
	v_or_b32_e32 v6, 0x3f00, v68
	v_add_u32_e32 v6, v30, v6
	v_mov_b32_e32 v100, v15
	ds_read_b32 v15, v6
	v_mov_b32_e32 v174, v67
	s_waitcnt lgkmcnt(2)
	v_mul_f32_e32 v163, v67, v12
	v_mov_b32_e32 v12, v31
	v_mov_b32_e32 v10, v29
	s_waitcnt lgkmcnt(0)
; DI float shx(float v, int k) { return __int_as_float(__builtin_amdgcn_ds_bpermute((lane_id_l() ^ k) << 2, __float_as_int(v))); }
; DI void diff_attn_item(const Params& P, const WsPtrs& W, int layer, int item, unsigned char* smem) {
;     ...
; #pragma unroll
;     for (int dt = 0; dt < 4; ++dt)
; #pragma unroll
;       for (int e = 0; e < 16; ++e) {
;         float v = o[dt][e] * inv - lam * ex[((w & 3) * 64 + dt * 16 + e) * 64 + lane];
;         o[dt][e] = v; ss += v * v;
;       }
;     ss += shx(ss, 32);
	v_pk_mul_f32 v[6:7], v[174:175], v[14:15] op_sel_hi:[0,1]
	v_pk_fma_f32 v[128:129], v[66:67], v[32:33], v[6:7] op_sel_hi:[0,1,1] neg_lo:[0,0,1] neg_hi:[0,0,1]
	v_mov_b32_e32 v6, v229
	v_pk_mul_f32 v[172:173], v[66:67], v[12:13]
	v_lshlrev_b32_e32 v6, 2, v6
	v_and_b32_e32 v0, 31, v162
	v_mov_b32_e32 v8, v26
	v_pk_mul_f32 v[166:167], v[66:67], v[10:11]
	v_xor_b32_e32 v43, 0x80, v6
	v_lshrrev_b32_e32 v6, 3, v162
	v_mov_b32_e32 v68, v172
	v_mov_b32_e32 v162, v173
	v_pk_mul_f32 v[126:127], v[66:67], v[8:9]
	v_pk_add_f32 v[68:69], v[68:69], v[162:163] neg_lo:[0,1] neg_hi:[0,1]
	v_mov_b32_e32 v162, v166
	v_mov_b32_e32 v163, v124
	v_mov_b32_e32 v124, v167
	v_pk_add_f32 v[124:125], v[162:163], v[124:125] neg_lo:[0,1] neg_hi:[0,1]
	v_mov_b32_e32 v162, v164
	v_mov_b32_e32 v163, v126
	v_mov_b32_e32 v126, v165
	v_mov_b32_e32 v132, v23
	v_pk_add_f32 v[126:127], v[162:163], v[126:127] neg_lo:[0,1] neg_hi:[0,1]
	v_mov_b32_e32 v162, v158
	v_mul_f32_e32 v158, v67, v133
	v_mov_b32_e32 v134, v21
	v_pk_fma_f32 v[132:133], v[66:67], v[132:133], v[158:159] op_sel_hi:[1,1,0] neg_lo:[0,0,1] neg_hi:[0,0,1]
	v_mul_f32_e32 v158, v67, v135
	v_mov_b32_e32 v136, v19
	v_pk_fma_f32 v[134:135], v[66:67], v[134:135], v[158:159] op_sel_hi:[1,1,0] neg_lo:[0,0,1] neg_hi:[0,0,1]
	v_mul_f32_e32 v158, v67, v137
	v_pk_fma_f32 v[136:137], v[66:67], v[136:137], v[158:159] op_sel_hi:[1,1,0] neg_lo:[0,0,1] neg_hi:[0,0,1]
	v_mul_f32_e32 v158, v67, v139
	v_pk_fma_f32 v[138:139], v[66:67], v[138:139], v[158:159] op_sel_hi:[1,1,0] neg_lo:[0,0,1] neg_hi:[0,0,1]
	v_mul_f32_e32 v158, v67, v141
	v_pk_fma_f32 v[140:141], v[66:67], v[140:141], v[158:159] op_sel_hi:[1,1,0] neg_lo:[0,0,1] neg_hi:[0,0,1]
	v_mul_f32_e32 v158, v67, v143
	v_pk_fma_f32 v[142:143], v[66:67], v[142:143], v[158:159] op_sel_hi:[1,1,0] neg_lo:[0,0,1] neg_hi:[0,0,1]
	v_mul_f32_e32 v158, v67, v145
	v_mov_b32_e32 v148, v41
	v_pk_fma_f32 v[144:145], v[66:67], v[144:145], v[158:159] op_sel_hi:[1,1,0] neg_lo:[0,0,1] neg_hi:[0,0,1]
	v_mul_f32_e32 v158, v67, v149
	v_mov_b32_e32 v150, v39
	v_pk_fma_f32 v[148:149], v[66:67], v[148:149], v[158:159] op_sel_hi:[1,1,0] neg_lo:[0,0,1] neg_hi:[0,0,1]
	v_mul_f32_e32 v158, v67, v151
	v_mov_b32_e32 v154, v37
	v_pk_fma_f32 v[150:151], v[66:67], v[150:151], v[158:159] op_sel_hi:[1,1,0] neg_lo:[0,0,1] neg_hi:[0,0,1]
	v_mul_f32_e32 v158, v67, v155
	v_mov_b32_e32 v156, v35
	v_pk_fma_f32 v[154:155], v[66:67], v[154:155], v[158:159] op_sel_hi:[1,1,0] neg_lo:[0,0,1] neg_hi:[0,0,1]
	v_mul_f32_e32 v158, v67, v157
	v_pk_fma_f32 v[156:157], v[66:67], v[156:157], v[158:159] op_sel_hi:[1,1,0] neg_lo:[0,0,1] neg_hi:[0,0,1]
	v_mul_f32_e32 v158, v67, v153
	v_pk_fma_f32 v[152:153], v[66:67], v[152:153], v[158:159] op_sel_hi:[1,1,0] neg_lo:[0,0,1] neg_hi:[0,0,1]
	v_mul_f32_e32 v158, v67, v147
	v_pk_fma_f32 v[146:147], v[66:67], v[146:147], v[158:159] op_sel_hi:[1,1,0] neg_lo:[0,0,1] neg_hi:[0,0,1]
	v_mul_f32_e32 v158, v67, v115
	v_mov_b32_e32 v163, v130
	v_mov_b32_e32 v130, v159
	v_pk_fma_f32 v[158:159], v[66:67], v[114:115], v[158:159] op_sel_hi:[1,1,0] neg_lo:[0,0,1] neg_hi:[0,0,1]
	v_mul_f32_e32 v114, v67, v113
	v_pk_add_f32 v[130:131], v[162:163], v[130:131] neg_lo:[0,1] neg_hi:[0,1]
	v_pk_fma_f32 v[162:163], v[66:67], v[112:113], v[114:115] op_sel_hi:[1,1,0] neg_lo:[0,0,1] neg_hi:[0,0,1]
	v_mul_f32_e32 v112, v67, v111
	v_pk_fma_f32 v[164:165], v[66:67], v[110:111], v[112:113] op_sel_hi:[1,1,0] neg_lo:[0,0,1] neg_hi:[0,0,1]
	v_mul_f32_e32 v110, v67, v109
	v_pk_fma_f32 v[166:167], v[66:67], v[108:109], v[110:111] op_sel_hi:[1,1,0] neg_lo:[0,0,1] neg_hi:[0,0,1]
	v_mul_f32_e32 v108, v67, v107
	v_pk_fma_f32 v[196:197], v[66:67], v[106:107], v[108:109] op_sel_hi:[1,1,0] neg_lo:[0,0,1] neg_hi:[0,0,1]
	v_mul_f32_e32 v106, v67, v105
	v_mov_b32_e32 v102, v17
	v_pk_fma_f32 v[198:199], v[66:67], v[104:105], v[106:107] op_sel_hi:[1,1,0] neg_lo:[0,0,1] neg_hi:[0,0,1]
	v_mul_f32_e32 v104, v67, v103
	v_pk_fma_f32 v[102:103], v[66:67], v[102:103], v[104:105] op_sel_hi:[1,1,0] neg_lo:[0,0,1] neg_hi:[0,0,1]
	v_mul_f32_e32 v104, v67, v101
	v_pk_fma_f32 v[100:101], v[66:67], v[100:101], v[104:105] op_sel_hi:[1,1,0] neg_lo:[0,0,1] neg_hi:[0,0,1]
	v_mul_f32_e32 v104, v67, v99
	v_pk_fma_f32 v[98:99], v[66:67], v[98:99], v[104:105] op_sel_hi:[1,1,0] neg_lo:[0,0,1] neg_hi:[0,0,1]
	v_mul_f32_e32 v104, v67, v97
	v_pk_fma_f32 v[96:97], v[66:67], v[96:97], v[104:105] op_sel_hi:[1,1,0] neg_lo:[0,0,1] neg_hi:[0,0,1]
	v_mul_f32_e32 v104, v67, v95
	v_pk_fma_f32 v[94:95], v[66:67], v[94:95], v[104:105] op_sel_hi:[1,1,0] neg_lo:[0,0,1] neg_hi:[0,0,1]
	v_mul_f32_e32 v104, v67, v89
	v_pk_mul_f32 v[92:93], v[174:175], v[92:93] op_sel_hi:[0,1]
	v_pk_mul_f32 v[90:91], v[90:91], v[174:175] op_sel_hi:[1,0]
	v_pk_fma_f32 v[88:89], v[66:67], v[88:89], v[104:105] op_sel_hi:[1,1,0] neg_lo:[0,0,1] neg_hi:[0,0,1]
	v_pk_fma_f32 v[92:93], v[66:67], v[4:5], v[92:93] op_sel_hi:[0,1,1] neg_lo:[0,0,1] neg_hi:[0,0,1]
	v_pk_fma_f32 v[66:67], v[66:67], v[2:3], v[90:91] op_sel_hi:[0,1,1] neg_lo:[0,0,1] neg_hi:[0,0,1]
	v_pk_mul_f32 v[2:3], v[66:67], v[66:67]
	v_pk_mul_f32 v[4:5], v[92:93], v[92:93]
	v_add_f32_e32 v2, v2, v3
	v_add_f32_e32 v2, v4, v2
	v_add_f32_e32 v2, v5, v2
	v_fmac_f32_e32 v2, v70, v70
	v_fmac_f32_e32 v2, v88, v88
	v_fmac_f32_e32 v2, v72, v72
	v_fmac_f32_e32 v2, v94, v94
	v_fmac_f32_e32 v2, v80, v80
	v_fmac_f32_e32 v2, v96, v96
	v_fmac_f32_e32 v2, v78, v78
	v_fmac_f32_e32 v2, v98, v98
	v_fmac_f32_e32 v2, v74, v74
	v_fmac_f32_e32 v2, v100, v100
	v_fmac_f32_e32 v2, v76, v76
	v_fmac_f32_e32 v2, v102, v102
	v_fmac_f32_e32 v2, v84, v84
	v_fmac_f32_e32 v2, v198, v198
	v_fmac_f32_e32 v2, v82, v82
	v_fmac_f32_e32 v2, v196, v196
	v_fmac_f32_e32 v2, v50, v50
; DI float shx(float v, int k) { return __int_as_float(__builtin_amdgcn_ds_bpermute((lane_id_l() ^ k) << 2, __float_as_int(v))); }
; DI void diff_attn_item(const Params& P, const WsPtrs& W, int layer, int item, unsigned char* smem) {
;     ...
;         o[dt][e] = v; ss += v * v;
;       }
;     ss += shx(ss, 32);
;     float sc = rsqrtf(ss * (1.f / 128.f) + EPSV) * (1.f - lam_init);
;     const float* sg = P.in[I_DSUBG] + layer * 128;
; #pragma unroll
;     for (int dt = 0; dt < 4; ++dt)
; #pragma unroll
;       for (int g = 0; g < 4; ++g) {
;         f32x4 g4 = *(const f32x4*)(sg + 32 * dt + 8 * g + 4 * h);
;         o[dt][4 * g] *= sc * g4.x; o[dt][4 * g + 1] *= sc * g4.y; o[dt][4 * g + 2] *= sc * g4.z; o[dt][4 * g + 3] *= sc * g4.w;
	v_fmac_f32_e32 v2, v166, v166
	v_fmac_f32_e32 v2, v52, v52
	v_fmac_f32_e32 v2, v164, v164
	v_fmac_f32_e32 v2, v86, v86
	v_fmac_f32_e32 v2, v162, v162
	v_fmac_f32_e32 v2, v58, v58
	v_fmac_f32_e32 v2, v158, v158
	v_fmac_f32_e32 v2, v54, v54
	v_fmac_f32_e32 v2, v146, v146
	v_fmac_f32_e32 v2, v56, v56
	v_fmac_f32_e32 v2, v152, v152
	v_fmac_f32_e32 v2, v116, v116
	v_fmac_f32_e32 v2, v156, v156
	v_fmac_f32_e32 v2, v64, v64
	v_fmac_f32_e32 v2, v154, v154
	v_fmac_f32_e32 v2, v60, v60
	v_fmac_f32_e32 v2, v150, v150
	v_fmac_f32_e32 v2, v62, v62
	v_fmac_f32_e32 v2, v148, v148
	v_fmac_f32_e32 v2, v120, v120
	v_fmac_f32_e32 v2, v144, v144
	v_fmac_f32_e32 v2, v118, v118
	v_fmac_f32_e32 v2, v142, v142
	v_fmac_f32_e32 v2, v42, v42
	v_fmac_f32_e32 v2, v140, v140
	v_fmac_f32_e32 v2, v44, v44
	v_fmac_f32_e32 v2, v138, v138
	v_fmac_f32_e32 v2, v122, v122
	v_fmac_f32_e32 v2, v136, v136
	v_fmac_f32_e32 v2, v48, v48
	v_fmac_f32_e32 v2, v134, v134
	v_fmac_f32_e32 v2, v46, v46
	v_pk_mul_f32 v[180:181], v[130:131], v[130:131]
	v_fmac_f32_e32 v2, v132, v132
	v_add_f32_e32 v2, v181, v2
	v_pk_mul_f32 v[178:179], v[126:127], v[126:127]
	v_add_f32_e32 v2, v180, v2
	v_add_f32_e32 v2, v179, v2
	v_pk_mul_f32 v[176:177], v[124:125], v[124:125]
	v_add_f32_e32 v2, v178, v2
	v_add_f32_e32 v2, v177, v2
	v_pk_mul_f32 v[172:173], v[68:69], v[68:69]
	v_add_f32_e32 v2, v176, v2
	v_add_f32_e32 v2, v173, v2
	v_pk_mul_f32 v[160:161], v[128:129], v[128:129]
	v_and_b32_e32 v170, 4, v6
	v_readlane_b32 s14, v255, 30
	v_add_f32_e32 v2, v172, v2
	v_lshlrev_b32_e32 v45, 2, v170
	v_readlane_b32 s15, v255, 31
	v_add_f32_e32 v2, v160, v2
	s_nop 3
	global_load_dwordx4 v[38:41], v45, s[14:15]
	global_load_dwordx4 v[34:37], v45, s[14:15] offset:32
	global_load_dwordx4 v[30:33], v45, s[14:15] offset:64
	global_load_dwordx4 v[26:29], v45, s[14:15] offset:96
	global_load_dwordx4 v[22:25], v45, s[14:15] offset:128
	global_load_dwordx4 v[18:21], v45, s[14:15] offset:160
	global_load_dwordx4 v[14:17], v45, s[14:15] offset:192
	global_load_dwordx4 v[10:13], v45, s[14:15] offset:224
	global_load_dwordx4 v[6:9], v45, s[14:15] offset:256
	v_add_f32_e32 v47, v161, v2
	global_load_dwordx4 v[2:5], v45, s[14:15] offset:288
	global_load_dwordx4 v[172:175], v45, s[14:15] offset:320
	global_load_dwordx4 v[176:179], v45, s[14:15] offset:352
	global_load_dwordx4 v[180:183], v45, s[14:15] offset:384
	global_load_dwordx4 v[184:187], v45, s[14:15] offset:416
	global_load_dwordx4 v[188:191], v45, s[14:15] offset:448
	global_load_dwordx4 v[192:195], v45, s[14:15] offset:480
	ds_bpermute_b32 v43, v43, v47
	s_mov_b32 s12, 0x800000
	v_sub_f32_e32 v49, 1.0, v169
	s_or_b64 s[4:5], s[4:5], exec
	s_waitcnt lgkmcnt(0)
	v_add_f32_e32 v43, v47, v43
	v_fmamk_f32 v43, v43, 0x3c000000, v228
	v_mul_f32_e32 v47, 0x4b800000, v43
	v_cmp_gt_f32_e32 vcc, s12, v43
	s_nop 1
	v_cndmask_b32_e32 v43, v43, v47, vcc
	v_rsq_f32_e32 v43, v43
	s_nop 0
	v_mul_f32_e32 v45, 0x45800000, v43
	v_cndmask_b32_e32 v43, v43, v45, vcc
	v_mul_f32_e32 v160, v49, v43
	s_waitcnt vmcnt(15)
	v_pk_mul_f32 v[38:39], v[38:39], v[160:161] op_sel_hi:[1,0]
	s_waitcnt vmcnt(14)
	v_mul_f32_e32 v34, v34, v160
	s_waitcnt vmcnt(13)
	v_mul_f32_e32 v30, v30, v160
	v_mul_f32_e32 v81, v31, v160
	v_mov_b32_e32 v31, v96
	s_waitcnt vmcnt(11)
	v_mul_f32_e32 v22, v22, v160
	v_mul_f32_e32 v85, v23, v160
	v_mov_b32_e32 v23, v198
	s_waitcnt vmcnt(6)
	v_mul_f32_e32 v2, v160, v2
	v_mul_f32_e32 v61, v160, v3
	v_mov_b32_e32 v3, v150
	v_pk_mul_f32 v[108:109], v[30:31], v[80:81]
	v_mul_f32_e32 v26, v26, v160
	v_mul_f32_e32 v75, v27, v160
	v_mov_b32_e32 v27, v100
	v_pk_mul_f32 v[100:101], v[22:23], v[84:85]
	v_mul_f32_e32 v22, v24, v160
	v_mul_f32_e32 v83, v25, v160
	v_mov_b32_e32 v23, v196
	v_pk_mul_f32 v[80:81], v[2:3], v[60:61]
	v_mul_f32_e32 v2, v160, v4
	v_mul_f32_e32 v63, v160, v5
	v_mov_b32_e32 v3, v148
	v_pk_mul_f32 v[104:105], v[26:27], v[74:75]
	v_mul_f32_e32 v26, v28, v160
	v_mul_f32_e32 v77, v29, v160
	v_mov_b32_e32 v27, v102
	v_pk_mul_f32 v[102:103], v[22:23], v[82:83]
	v_pk_mul_f32 v[82:83], v[2:3], v[62:63]
	s_waitcnt vmcnt(5)
; DI void diff_attn_item(const Params& P, const WsPtrs& W, int layer, int item, unsigned char* smem) {
;     ...
;     float sc = rsqrtf(ss * (1.f / 128.f) + EPSV) * (1.f - lam_init);
;     const float* sg = P.in[I_DSUBG] + layer * 128;
; #pragma unroll
;     for (int dt = 0; dt < 4; ++dt)
; #pragma unroll
;       for (int g = 0; g < 4; ++g) {
;         f32x4 g4 = *(const f32x4*)(sg + 32 * dt + 8 * g + 4 * h);
;         o[dt][4 * g] *= sc * g4.x; o[dt][4 * g + 1] *= sc * g4.y; o[dt][4 * g + 2] *= sc * g4.z; o[dt][4 * g + 3] *= sc * g4.w;
;       }
;     store_o(o, W.YMIX + (tokb + q0 + r) * 4096 + 1024 + hh * 128, h);
	v_mul_f32_e32 v2, v160, v172
	v_mul_f32_e32 v121, v160, v173
	v_mov_b32_e32 v3, v144
	v_mul_f32_e32 v71, v35, v160
	v_mov_b32_e32 v35, v88
	v_mul_f32_e32 v30, v32, v160
	v_mul_f32_e32 v79, v33, v160
	v_mov_b32_e32 v31, v98
	v_pk_mul_f32 v[106:107], v[26:27], v[76:77]
	v_pk_mul_f32 v[76:77], v[2:3], v[120:121]
	v_mul_f32_e32 v2, v160, v174
	v_mul_f32_e32 v119, v160, v175
	v_mov_b32_e32 v3, v142
	v_pk_mul_f32 v[112:113], v[34:35], v[70:71]
	v_mul_f32_e32 v34, v36, v160
	v_mul_f32_e32 v73, v37, v160
	v_mov_b32_e32 v35, v94
	v_pk_mul_f32 v[110:111], v[30:31], v[78:79]
	v_pk_mul_f32 v[78:79], v[2:3], v[118:119]
	s_waitcnt vmcnt(4)
	v_mul_f32_e32 v2, v160, v176
	v_mul_f32_e32 v43, v160, v177
	v_mov_b32_e32 v3, v140
	v_pk_mul_f32 v[114:115], v[34:35], v[72:73]
	v_pk_mul_f32 v[72:73], v[2:3], v[42:43]
	v_mul_f32_e32 v2, v160, v178
	v_mul_f32_e32 v45, v160, v179
	v_mov_b32_e32 v3, v138
	v_mul_f32_e32 v6, v6, v160
	v_mul_f32_e32 v117, v7, v160
	v_mov_b32_e32 v7, v156
	v_pk_mul_f32 v[74:75], v[2:3], v[44:45]
	s_waitcnt vmcnt(3)
	v_mul_f32_e32 v2, v160, v180
	v_mul_f32_e32 v123, v160, v181
	v_mov_b32_e32 v3, v136
	v_pk_mul_f32 v[84:85], v[6:7], v[116:117]
	v_pk_mul_f32 v[116:117], v[2:3], v[122:123]
	v_mul_f32_e32 v2, v160, v182
	v_mul_f32_e32 v49, v160, v183
	v_mov_b32_e32 v3, v134
	v_pk_mul_f32 v[70:71], v[2:3], v[48:49]
	s_waitcnt vmcnt(2)
	v_mul_f32_e32 v2, v160, v184
	v_mul_f32_e32 v47, v160, v185
	v_mov_b32_e32 v3, v132
	v_pk_mul_f32 v[118:119], v[2:3], v[46:47]
	v_mul_f32_e32 v2, v160, v186
	v_mul_f32_e32 v5, v160, v187
	v_mov_b32_e32 v3, v130
	v_mov_b32_e32 v4, v131
	v_pk_mul_f32 v[134:135], v[2:3], v[4:5]
	s_waitcnt vmcnt(1)
	v_mul_f32_e32 v2, v160, v188
	v_mul_f32_e32 v5, v160, v189
	v_mov_b32_e32 v3, v126
	v_mov_b32_e32 v4, v127
	v_pk_mul_f32 v[130:131], v[2:3], v[4:5]
	v_mul_f32_e32 v2, v160, v190
	v_mul_f32_e32 v5, v160, v191
	v_mov_b32_e32 v3, v124
	v_mov_b32_e32 v4, v125
	v_pk_mul_f32 v[126:127], v[2:3], v[4:5]
	s_waitcnt vmcnt(0)
	v_mul_f32_e32 v2, v160, v192
	v_mul_f32_e32 v5, v160, v193
	v_mov_b32_e32 v3, v68
	v_mov_b32_e32 v4, v69
	v_pk_mul_f32 v[124:125], v[2:3], v[4:5]
	v_pk_mul_f32 v[2:3], v[160:161], v[194:195] op_sel_hi:[0,1]
	v_pk_mul_f32 v[122:123], v[128:129], v[2:3]
	v_or3_b32 v2, v168, v0, s6
	v_mov_b32_e32 v3, s7
	v_lshlrev_b64 v[2:3], 13, v[2:3]
	v_lshl_add_u64 v[2:3], s[8:9], 0, v[2:3]
	v_pk_mul_f32 v[40:41], v[40:41], v[160:161] op_sel_hi:[1,0]
	v_mul_f32_e32 v18, v18, v160
	v_mul_f32_e32 v51, v19, v160
	v_mov_b32_e32 v19, v166
	v_mul_f32_e32 v14, v14, v160
	v_mul_f32_e32 v87, v15, v160
	v_mov_b32_e32 v15, v162
	v_mul_f32_e32 v10, v10, v160
	v_mul_f32_e32 v55, v11, v160
	v_mov_b32_e32 v11, v146
	v_lshl_add_u64 v[2:3], v[2:3], 0, s[2:3]
	v_lshlrev_b32_e32 v0, 1, v170
	v_pk_mul_f32 v[38:39], v[66:67], v[38:39]
	v_pk_mul_f32 v[40:41], v[92:93], v[40:41]
	v_pk_mul_f32 v[96:97], v[18:19], v[50:51]
	v_mul_f32_e32 v18, v20, v160
	v_mul_f32_e32 v53, v21, v160
	v_mov_b32_e32 v19, v164
	v_pk_mul_f32 v[92:93], v[14:15], v[86:87]
	v_mul_f32_e32 v14, v16, v160
	v_mul_f32_e32 v59, v17, v160
	v_mov_b32_e32 v15, v158
	v_pk_mul_f32 v[88:89], v[10:11], v[54:55]
	v_mul_f32_e32 v10, v12, v160
	v_mul_f32_e32 v57, v13, v160
	v_mov_b32_e32 v11, v152
	v_mul_f32_e32 v6, v8, v160
	v_mul_f32_e32 v65, v9, v160
	v_mov_b32_e32 v7, v154
	v_lshl_add_u64 v[2:3], v[2:3], 0, v[0:1]
	s_mov_b64 s[6:7], 0x800
	v_pk_mul_f32 v[98:99], v[18:19], v[52:53]
	v_pk_mul_f32 v[94:95], v[14:15], v[58:59]
	v_pk_mul_f32 v[90:91], v[10:11], v[56:57]
	v_pk_mul_f32 v[86:87], v[6:7], v[64:65]
	v_lshl_add_u64 v[120:121], v[2:3], 0, s[6:7]
	v_cvt_pk_bf16_f32 v4, v38, v39
	v_cvt_pk_bf16_f32 v5, v40, v41
	global_store_dwordx2 v[2:3], v[4:5], off offset:2048

; #define MFMA32(a, b, c) __builtin_amdgcn_mfma_f32_32x32x16_bf16((a), (b), (c), 0, 0, 0)
;     ...
;       for (int g = 0; g < NBAT; ++g) {
;         if (g + 1 < NBAT) {
;           const int t2n = (g + 1) / BPT, bn = (g + 1) % BPT;
; #pragma unroll
;           for (int i = 0; i < 4; ++i) kf[(g + 1) & 1][i] = *(const bf16x8*)(Ks + (32 * t2n + r) * KST + kcol_off + 16 * (4 * bn + i) + 8 * h);
;         }
;         __builtin_amdgcn_sched_barrier(0);
;         const int t2 = g / BPT, b = g % BPT;
; #pragma unroll
;         for (int i = 0; i < 4; ++i) st[t2] = MFMA32(kf[g & 1][i], qf[4 * b + i], st[t2]);
;         __builtin_amdgcn_sched_barrier(0);
;       }
;     }
;     bf16x8 vf[2][4];
; #pragma unroll
;     for (int dt = 0; dt < 4; ++dt) vf[0][dt] = *(const bf16x8*)(Vs + (32 * dt + r) * 72 + 8 * h);
;     if (MODE == 2) {
;       const float kb = (float)((kt0 + kt) * 64 + 4 * h);
; #pragma unroll
;       for (int t2 = 0; t2 < 2; ++t2)
; #pragma unroll
;         for (int e = 0; e < 16; ++e) {
;           float kp = kb + (float)(32 * t2 + (e & 3) + 8 * (e >> 2));
;           st[t2][e] *= __builtin_amdgcn_exp2f(dl * fabsf(qpos - kp));
;         }
;     } else if (MODE == 1) {
;       float ls = 0.f;
; #pragma unroll
;       for (int t2 = 0; t2 < 2; ++t2)
; #pragma unroll
;         for (int e = 0; e < 16; ++e) { float p = __builtin_amdgcn_exp2f(st[t2][e]); st[t2][e] = p; ls += p; }
;       l_run += ls;
;     } else {
;       float mx = st[0][0];
; #pragma unroll
;       for (int t2 = 0; t2 < 2; ++t2)
; #pragma unroll
;         for (int e = 0; e < 16; ++e) mx = fmaxf(mx, st[t2][e]);
;       mx = fmaxf(mx, shx(mx, 32));
;       float mnew = fmaxf(m_run, mx);
;       float alpha = __builtin_amdgcn_exp2f(m_run - mnew);
;       const bool changed = mnew > m_run;
;       m_run = mnew;
;       float ls = 0.f;
; #pragma unroll
;       for (int t2 = 0; t2 < 2; ++t2)
; #pragma unroll
;         for (int e = 0; e < 16; ++e) { float p = __builtin_amdgcn_exp2f(st[t2][e] - mnew); st[t2][e] = p; ls += p; }
;       l_run = l_run * alpha + ls;
;       if (__any(changed)) {
; #pragma unroll
;         for (int dt = 0; dt < 4; ++dt)
; #pragma unroll
;           for (int e = 0; e < 16; ++e) o[dt][e] *= alpha;
;       }
;     }
; #pragma unroll
;     for (int c = 0; c < 4; ++c) {
;       const int t2 = c >> 1, s2 = c & 1;
;       if (c + 1 < 4) {
; #pragma unroll
.Lmla_skip_gb:
	s_waitcnt lgkmcnt(8)
	v_mfma_f32_32x32x16_bf16 v[82:97], v[200:203], v[130:133], v[82:97]
	ds_read_b128 v[200:203], v220 offset:12800
	v_lshl_add_u64 v[192:193], v[192:193], 0, s[30:31]
	s_waitcnt lgkmcnt(8)
	v_mfma_f32_32x32x16_bf16 v[82:97], v[204:207], v[134:137], v[82:97]
	ds_read_b128 v[204:207], v220 offset:12832
	v_lshl_add_u64 v[194:195], v[194:195], 0, s[92:93]
	s_waitcnt lgkmcnt(8)
	v_mfma_f32_32x32x16_bf16 v[82:97], v[208:211], v[138:141], v[82:97]
	ds_read_b128 v[208:211], v220 offset:12864
	v_lshl_add_u64 v[196:197], v[196:197], 0, s[92:93]
	s_waitcnt lgkmcnt(6)
	v_mfma_f32_32x32x16_bf16 v[82:97], v[212:215], v[142:145], v[82:97]
	ds_read_b128 v[212:215], v220 offset:12896
	v_lshl_add_u64 v[198:199], v[198:199], 0, s[92:93]
	v_mfma_f32_32x32x16_bf16 v[82:97], v[216:219], v[146:149], v[82:97]
	ds_read_b128 v[216:219], v220 offset:12928
	v_mfma_f32_32x32x16_bf16 v[82:97], v[224:227], v[154:157], v[82:97]
	ds_read_b128 v[224:227], v220 offset:12960
	v_mfma_f32_32x32x16_bf16 v[82:97], v[230:233], v[150:153], v[82:97]
	ds_read_b128 v[230:233], v220 offset:12992
	v_mfma_f32_32x32x16_bf16 v[82:97], v[238:241], v[158:161], v[82:97]
	ds_read_b128 v[238:241], v220 offset:13024
	s_waitcnt lgkmcnt(7)
	v_mfma_f32_32x32x16_bf16 v[98:113], v[200:203], v[114:117], v[66:81]
	ds_read_b128 v[200:203], v220 offset:13056
	s_waitcnt lgkmcnt(7)
	v_mfma_f32_32x32x16_bf16 v[98:113], v[204:207], v[118:121], v[98:113]
	ds_read_b128 v[204:207], v220 offset:13088
	s_waitcnt lgkmcnt(7)
	v_mfma_f32_32x32x16_bf16 v[98:113], v[208:211], v[122:125], v[98:113]
	ds_read_b128 v[208:211], v220 offset:13120
	s_waitcnt lgkmcnt(7)
	v_mfma_f32_32x32x16_bf16 v[98:113], v[212:215], v[126:129], v[98:113]
	ds_read_b128 v[212:215], v220 offset:13152
	v_add_u32_e32 v220, v220, v189
	v_exp_f32_e32 v82, v82
	v_exp_f32_e32 v83, v83
	s_waitcnt lgkmcnt(7)
	v_mfma_f32_32x32x16_bf16 v[98:113], v[216:219], v[130:133], v[98:113]
	ds_read_b128 v[216:219], v220 offset:25600
	v_exp_f32_e32 v84, v84
	v_exp_f32_e32 v85, v85
	s_waitcnt lgkmcnt(7)
	v_mfma_f32_32x32x16_bf16 v[98:113], v[224:227], v[134:137], v[98:113]
	ds_read_b128 v[224:227], v220 offset:30208
	v_exp_f32_e32 v86, v86
	v_exp_f32_e32 v87, v87
	s_waitcnt lgkmcnt(7)
	v_mfma_f32_32x32x16_bf16 v[98:113], v[230:233], v[138:141], v[98:113]
	ds_read_b128 v[230:233], v220 offset:34816
	v_exp_f32_e32 v88, v88
	v_exp_f32_e32 v89, v89
	s_waitcnt lgkmcnt(7)
	v_mfma_f32_32x32x16_bf16 v[98:113], v[238:241], v[142:145], v[98:113]
	ds_read_b128 v[238:241], v220 offset:39424
	v_exp_f32_e32 v90, v90
	v_exp_f32_e32 v91, v91
	v_cvt_pk_bf16_f32 v242, v82, v83
	s_waitcnt lgkmcnt(7)
	v_mfma_f32_32x32x16_bf16 v[98:113], v[200:203], v[146:149], v[98:113]
	ds_read_b128 v[200:203], v220 offset:25632
	v_exp_f32_e32 v92, v92
	v_exp_f32_e32 v93, v93
	v_cvt_pk_bf16_f32 v243, v84, v85
	s_waitcnt lgkmcnt(7)
	v_mfma_f32_32x32x16_bf16 v[98:113], v[204:207], v[154:157], v[98:113]
	ds_read_b128 v[204:207], v220 offset:30240
	v_exp_f32_e32 v94, v94
	v_exp_f32_e32 v95, v95
	v_cvt_pk_bf16_f32 v244, v86, v87
	s_waitcnt lgkmcnt(7)
	v_mfma_f32_32x32x16_bf16 v[98:113], v[208:211], v[150:153], v[98:113]
	ds_read_b128 v[208:211], v220 offset:34848
	v_exp_f32_e32 v96, v96
	v_exp_f32_e32 v97, v97
	v_cvt_pk_bf16_f32 v245, v88, v89
	s_waitcnt lgkmcnt(7)
	v_mfma_f32_32x32x16_bf16 v[98:113], v[212:215], v[158:161], v[98:113]
	ds_read_b128 v[212:215], v220 offset:39456
	v_add_f32_e32 v246, v90, v91
	v_add_f32_e32 v246, v92, v246
	v_add_f32_e32 v246, v93, v246
	v_add_f32_e32 v246, v94, v246
	s_waitcnt lgkmcnt(7)
	v_mfma_f32_32x32x16_bf16 v[50:65], v[216:219], v[242:245], v[50:65]
	ds_read_b128 v[216:219], v220 offset:25664
	v_add_f32_e32 v246, v95, v246
	v_add_f32_e32 v246, v96, v246
	v_add_f32_e32 v246, v97, v246
	v_cvt_pk_bf16_f32 v90, v90, v91
	v_cvt_pk_bf16_f32 v91, v92, v93
	s_waitcnt lgkmcnt(7)
	v_mfma_f32_32x32x16_bf16 v[34:49], v[224:227], v[242:245], v[34:49]
	ds_read_b128 v[224:227], v220 offset:30272
	v_cvt_pk_bf16_f32 v92, v94, v95
	v_cvt_pk_bf16_f32 v93, v96, v97
	v_exp_f32_e32 v98, v98
	v_exp_f32_e32 v99, v99
	s_waitcnt lgkmcnt(7)
	v_mfma_f32_32x32x16_bf16 v[18:33], v[230:233], v[242:245], v[18:33]
	ds_read_b128 v[230:233], v220 offset:34880
	v_exp_f32_e32 v100, v100
	v_exp_f32_e32 v101, v101
	v_exp_f32_e32 v102, v102
	s_waitcnt lgkmcnt(7)
	v_mfma_f32_32x32x16_bf16 v[2:17], v[238:241], v[242:245], v[2:17]
	ds_read_b128 v[238:241], v220 offset:39488
	v_exp_f32_e32 v103, v103
	v_exp_f32_e32 v104, v104
	v_exp_f32_e32 v105, v105
	s_waitcnt lgkmcnt(7)
	v_mfma_f32_32x32x16_bf16 v[50:65], v[200:203], v[90:93], v[50:65]
	ds_read_b128 v[200:203], v220 offset:25696
	v_cvt_pk_bf16_f32 v94, v98, v99
	v_cvt_pk_bf16_f32 v95, v100, v101
	v_cvt_pk_bf16_f32 v96, v102, v103
	v_cvt_pk_bf16_f32 v97, v104, v105
	v_exp_f32_e32 v106, v106
	s_waitcnt lgkmcnt(7)
	v_mfma_f32_32x32x16_bf16 v[34:49], v[204:207], v[90:93], v[34:49]
	ds_read_b128 v[204:207], v220 offset:30304
	v_exp_f32_e32 v107, v107
	v_exp_f32_e32 v108, v108
	v_exp_f32_e32 v109, v109
	v_add_f32_e32 v246, v82, v246
	s_waitcnt lgkmcnt(7)
	v_mfma_f32_32x32x16_bf16 v[18:33], v[208:211], v[90:93], v[18:33]
	ds_read_b128 v[208:211], v220 offset:34912
	v_exp_f32_e32 v110, v110
	v_exp_f32_e32 v111, v111
	v_exp_f32_e32 v112, v112
	v_add_f32_e32 v246, v83, v246
	s_waitcnt lgkmcnt(7)
	v_mfma_f32_32x32x16_bf16 v[2:17], v[212:215], v[90:93], v[2:17]
	ds_read_b128 v[212:215], v220 offset:39520
	v_exp_f32_e32 v113, v113
	v_add_f32_e32 v247, v106, v107
	v_add_f32_e32 v247, v108, v247
	v_add_f32_e32 v246, v84, v246
	s_waitcnt lgkmcnt(7)
	v_mfma_f32_32x32x16_bf16 v[50:65], v[216:219], v[94:97], v[50:65]
	v_add_f32_e32 v247, v109, v247
	v_add_f32_e32 v247, v110, v247
	v_add_f32_e32 v247, v111, v247
	v_add_f32_e32 v247, v112, v247
	v_add_f32_e32 v247, v113, v247
	v_add_f32_e32 v246, v85, v246
	s_waitcnt lgkmcnt(6)
	v_mfma_f32_32x32x16_bf16 v[34:49], v[224:227], v[94:97], v[34:49]
	v_cvt_pk_bf16_f32 v242, v106, v107
	v_cvt_pk_bf16_f32 v243, v108, v109
	v_cvt_pk_bf16_f32 v244, v110, v111
	v_cvt_pk_bf16_f32 v245, v112, v113
	v_add_f32_e32 v247, v98, v247
	v_add_f32_e32 v246, v86, v246
	v_add_f32_e32 v247, v99, v247
	s_waitcnt lgkmcnt(5)
	v_mfma_f32_32x32x16_bf16 v[18:33], v[230:233], v[94:97], v[18:33]
	v_add_f32_e32 v247, v100, v247
	v_add_f32_e32 v246, v87, v246
	v_add_f32_e32 v247, v101, v247
	v_add_f32_e32 v246, v88, v246
	v_add_f32_e32 v247, v102, v247
	v_add_f32_e32 v246, v89, v246
	v_add_f32_e32 v247, v103, v247
	s_waitcnt lgkmcnt(4)
	v_mfma_f32_32x32x16_bf16 v[2:17], v[238:241], v[94:97], v[2:17]
	v_add_f32_e32 v247, v104, v247
	v_add_f32_e32 v247, v105, v247
	v_add_f32_e32 v246, v247, v246
	v_add_f32_e32 v185, v185, v246
	s_cmp_lg_u32 s22, 64
	s_waitcnt lgkmcnt(0)
	s_mov_b32 s21, s22
	s_barrier
	s_cbranch_scc1 .LBB0_590
